# attention tail: 13 of the 16 gate loads issued at the top of the last tile's exp block (4 address VGPRs + immediate offsets), same issue order
# speedup vs baseline: 1.0000x; 1.0000x over previous
.LBB0_420:
	v_or_b32_e32 v120, v180, v179
	v_lshlrev_b32_e32 v120, 1, v120
	v_add_u32_e32 v121, 0x4000, v120
	v_add_u32_e32 v122, 0x8000, v120
	v_add_u32_e32 v123, 0xc000, v120
	global_load_dwordx2 v[176:177], v120, s[6:7]
	global_load_dwordx2 v[174:175], v121, s[6:7]
	global_load_dwordx2 v[172:173], v122, s[6:7]
	global_load_dwordx2 v[170:171], v123, s[6:7]
	global_load_dwordx2 v[168:169], v120, s[6:7] offset:64
	global_load_dwordx2 v[166:167], v121, s[6:7] offset:64
	global_load_dwordx2 v[164:165], v122, s[6:7] offset:64
	global_load_dwordx2 v[162:163], v123, s[6:7] offset:64
	global_load_dwordx2 v[128:129], v120, s[6:7] offset:128
	global_load_dwordx2 v[126:127], v121, s[6:7] offset:128
	global_load_dwordx2 v[124:125], v122, s[6:7] offset:128
	global_load_dwordx2 v[122:123], v123, s[6:7] offset:128
	global_load_dwordx2 v[120:121], v120, s[6:7] offset:192
	v_cndmask_b32_e64 v114, v114, v182, s[4:5]
	v_mul_f32_e32 v114, 0xbe0293ee, v114
	v_fmamk_f32 v50, v50, 0x3e0293ee, v114
	v_fmamk_f32 v51, v51, 0x3e0293ee, v114
	v_exp_f32_e32 v50, v50
	v_fmamk_f32 v52, v52, 0x3e0293ee, v114
	v_fmamk_f32 v119, v65, 0x3e0293ee, v114
	v_exp_f32_e32 v65, v51
	v_fmamk_f32 v53, v53, 0x3e0293ee, v114
	v_exp_f32_e32 v51, v52
	v_fmamk_f32 v54, v54, 0x3e0293ee, v114
	v_fmamk_f32 v55, v55, 0x3e0293ee, v114
	v_fmamk_f32 v56, v56, 0x3e0293ee, v114
	v_fmamk_f32 v57, v57, 0x3e0293ee, v114
	v_fmamk_f32 v58, v58, 0x3e0293ee, v114
	v_fmamk_f32 v59, v59, 0x3e0293ee, v114
	v_fmamk_f32 v60, v60, 0x3e0293ee, v114
	v_fmamk_f32 v115, v61, 0x3e0293ee, v114
	v_fmamk_f32 v116, v62, 0x3e0293ee, v114
	v_fmamk_f32 v117, v63, 0x3e0293ee, v114
	v_fmamk_f32 v118, v64, 0x3e0293ee, v114
	v_fmamk_f32 v82, v82, 0x3e0293ee, v114
	v_fmamk_f32 v83, v83, 0x3e0293ee, v114
	v_fmamk_f32 v84, v84, 0x3e0293ee, v114
	v_fmamk_f32 v85, v85, 0x3e0293ee, v114
	v_fmamk_f32 v86, v86, 0x3e0293ee, v114
	v_fmamk_f32 v87, v87, 0x3e0293ee, v114
	v_fmamk_f32 v88, v88, 0x3e0293ee, v114
	v_fmamk_f32 v89, v89, 0x3e0293ee, v114
	v_fmamk_f32 v90, v90, 0x3e0293ee, v114
	v_fmamk_f32 v91, v91, 0x3e0293ee, v114
	v_fmamk_f32 v92, v92, 0x3e0293ee, v114
	v_fmamk_f32 v93, v93, 0x3e0293ee, v114
	v_fmamk_f32 v94, v94, 0x3e0293ee, v114
	v_exp_f32_e32 v64, v53
	v_fmamk_f32 v95, v95, 0x3e0293ee, v114
	v_fmamk_f32 v96, v96, 0x3e0293ee, v114
	v_fmac_f32_e32 v114, 0x3e0293ee, v97
	v_exp_f32_e32 v52, v54
	v_exp_f32_e32 v97, v114
	v_add_f32_e32 v114, 0, v50
	v_exp_f32_e32 v63, v55
	v_add_f32_e32 v114, v65, v114
	v_exp_f32_e32 v53, v56
	v_add_f32_e32 v114, v51, v114
	v_exp_f32_e32 v62, v57
	v_add_f32_e32 v114, v64, v114
	v_exp_f32_e32 v54, v58
	v_add_f32_e32 v114, v52, v114
	v_exp_f32_e32 v61, v59
	v_add_f32_e32 v114, v63, v114
	v_exp_f32_e32 v55, v60
	v_add_f32_e32 v114, v53, v114
	v_exp_f32_e32 v60, v115
	v_add_f32_e32 v114, v62, v114
	v_exp_f32_e32 v56, v116
	v_add_f32_e32 v114, v54, v114
	v_exp_f32_e32 v59, v117
	v_add_f32_e32 v114, v61, v114
	v_exp_f32_e32 v57, v118
	v_add_f32_e32 v114, v55, v114
	v_exp_f32_e32 v58, v119
	v_add_f32_e32 v114, v60, v114
	v_exp_f32_e32 v82, v82
	v_add_f32_e32 v114, v56, v114
	v_exp_f32_e32 v83, v83
	v_add_f32_e32 v114, v59, v114
	v_exp_f32_e32 v84, v84
	v_add_f32_e32 v114, v57, v114
	v_exp_f32_e32 v85, v85
	v_add_f32_e32 v114, v58, v114
	v_exp_f32_e32 v86, v86
	v_add_f32_e32 v114, v82, v114
	v_exp_f32_e32 v87, v87
	v_add_f32_e32 v114, v83, v114
	v_exp_f32_e32 v88, v88
	v_add_f32_e32 v114, v84, v114
	v_exp_f32_e32 v89, v89
	v_add_f32_e32 v114, v85, v114
	v_exp_f32_e32 v90, v90
	v_add_f32_e32 v114, v86, v114
	v_exp_f32_e32 v91, v91
	v_add_f32_e32 v114, v87, v114
	v_exp_f32_e32 v92, v92
	v_add_f32_e32 v114, v88, v114
	v_exp_f32_e32 v93, v93
	v_add_f32_e32 v114, v89, v114
	v_exp_f32_e32 v94, v94
	v_add_f32_e32 v114, v90, v114
	v_exp_f32_e32 v95, v95
	v_add_f32_e32 v114, v91, v114
	v_exp_f32_e32 v96, v96
	v_add_f32_e32 v114, v92, v114
	v_add_f32_e32 v114, v93, v114
	v_add_f32_e32 v114, v94, v114
	v_add_f32_e32 v114, v95, v114
	v_add_f32_e32 v114, v96, v114
	v_add_f32_e32 v182, v97, v114
	v_mov_b32_e32 v183, v182
	v_cvt_pk_bf16_f32 v50, v50, v65
	v_cvt_pk_bf16_f32 v51, v51, v64
	v_cvt_pk_bf16_f32 v52, v52, v63
	v_cvt_pk_bf16_f32 v53, v53, v62
	v_cvt_pk_bf16_f32 v54, v54, v61
	v_cvt_pk_bf16_f32 v55, v55, v60
	v_cvt_pk_bf16_f32 v56, v56, v59
	v_cvt_pk_bf16_f32 v57, v57, v58
	v_cvt_pk_bf16_f32 v58, v82, v83
	v_cvt_pk_bf16_f32 v59, v84, v85
	v_cvt_pk_bf16_f32 v60, v86, v87
	v_cvt_pk_bf16_f32 v61, v88, v89
	v_cvt_pk_bf16_f32 v62, v90, v91
	v_cvt_pk_bf16_f32 v63, v92, v93
	v_cvt_pk_bf16_f32 v64, v94, v95
	v_cvt_pk_bf16_f32 v65, v96, v97
	s_nop 1
	v_permlane32_swap_b32_e32 v182, v183
	v_permlane32_swap_b32_e32 v50, v52
	v_permlane32_swap_b32_e32 v51, v53
	v_permlane32_swap_b32_e32 v54, v56
	v_permlane32_swap_b32_e32 v55, v57
	v_permlane32_swap_b32_e32 v58, v60
	v_permlane32_swap_b32_e32 v59, v61
	v_permlane32_swap_b32_e32 v62, v64
	v_permlane32_swap_b32_e32 v63, v65
	v_or_b32_e32 v82, v180, v179
	v_lshlrev_b32_e32 v82, 1, v82
	v_add_u32_e32 v83, 0x4000, v82
	v_add_u32_e32 v84, 0x8000, v82
	v_add_u32_e32 v85, 0xc000, v82
	global_load_dwordx2 v[118:119], v83, s[6:7] offset:192
	global_load_dwordx2 v[116:117], v84, s[6:7] offset:192
	global_load_dwordx2 v[114:115], v85, s[6:7] offset:192
	v_add_f32_e32 v186, v182, v183
	v_fmac_f32_e32 v186, v181, v178
	ds_read_b64_tr_b16 v[82:83], v209 offset:0x4000
	ds_read_b64_tr_b16 v[84:85], v209 offset:0x4800
	ds_read_b64_tr_b16 v[86:87], v209 offset:0x5000
	ds_read_b64_tr_b16 v[88:89], v209 offset:0x5800
	ds_read_b64_tr_b16 v[90:91], v209 offset:0x6000
	ds_read_b64_tr_b16 v[92:93], v209 offset:0x6800
	ds_read_b64_tr_b16 v[94:95], v209 offset:0x7000
	ds_read_b64_tr_b16 v[96:97], v209 offset:0x7800
	s_waitcnt lgkmcnt(0)
	s_nop 0
	v_mfma_f32_32x32x16_bf16 v[66:81], v[50:53], v[82:85], v[66:81]
	ds_read_b64_tr_b16 v[82:83], v209 offset:0x4200
	ds_read_b64_tr_b16 v[84:85], v209 offset:0x4a00
	v_mfma_f32_32x32x16_bf16 v[66:81], v[54:57], v[86:89], v[66:81]
	ds_read_b64_tr_b16 v[86:87], v209 offset:0x5200
	ds_read_b64_tr_b16 v[88:89], v209 offset:0x5a00
	v_mfma_f32_32x32x16_bf16 v[66:81], v[58:61], v[90:93], v[66:81]
	ds_read_b64_tr_b16 v[90:91], v209 offset:0x6200
	ds_read_b64_tr_b16 v[92:93], v209 offset:0x6a00
	ds_read_b64_tr_b16 v[178:179], v209 offset:0x7200
	ds_read_b64_tr_b16 v[180:181], v209 offset:0x7a00
	s_waitcnt lgkmcnt(0)
	v_mfma_f32_32x32x16_bf16 v[66:81], v[62:65], v[94:97], v[66:81]
	v_mfma_f32_32x32x16_bf16 v[34:49], v[50:53], v[82:85], v[34:49]
	ds_read_b64_tr_b16 v[82:83], v209 offset:0x4400
	ds_read_b64_tr_b16 v[84:85], v209 offset:0x4c00
	v_mfma_f32_32x32x16_bf16 v[34:49], v[54:57], v[86:89], v[34:49]
	ds_read_b64_tr_b16 v[86:87], v209 offset:0x5400
	ds_read_b64_tr_b16 v[88:89], v209 offset:0x5c00
	v_mfma_f32_32x32x16_bf16 v[34:49], v[58:61], v[90:93], v[34:49]
	ds_read_b64_tr_b16 v[90:91], v209 offset:0x6400
	ds_read_b64_tr_b16 v[92:93], v209 offset:0x6c00
	ds_read_b64_tr_b16 v[94:95], v209 offset:0x7400
	ds_read_b64_tr_b16 v[96:97], v209 offset:0x7c00
	s_waitcnt lgkmcnt(0)
	v_mfma_f32_32x32x16_bf16 v[34:49], v[62:65], v[178:181], v[34:49]
	v_mfma_f32_32x32x16_bf16 v[18:33], v[50:53], v[82:85], v[18:33]
	ds_read_b64_tr_b16 v[82:83], v209 offset:0x4600
	ds_read_b64_tr_b16 v[84:85], v209 offset:0x4e00
	v_mfma_f32_32x32x16_bf16 v[18:33], v[54:57], v[86:89], v[18:33]
	ds_read_b64_tr_b16 v[86:87], v209 offset:0x5600
	ds_read_b64_tr_b16 v[88:89], v209 offset:0x5e00
	v_mfma_f32_32x32x16_bf16 v[18:33], v[58:61], v[90:93], v[18:33]
	ds_read_b64_tr_b16 v[90:91], v209 offset:0x6600
	ds_read_b64_tr_b16 v[92:93], v209 offset:0x6e00
	ds_read_b64_tr_b16 v[182:183], v209 offset:0x7600
	ds_read_b64_tr_b16 v[184:185], v209 offset:0x7e00
	s_waitcnt lgkmcnt(0)
	v_mfma_f32_32x32x16_bf16 v[18:33], v[62:65], v[94:97], v[18:33]
	v_mfma_f32_32x32x16_bf16 v[2:17], v[50:53], v[82:85], v[2:17]
	v_mov_b32_e32 v181, v186
	v_mfma_f32_32x32x16_bf16 v[2:17], v[54:57], v[86:89], v[2:17]
	v_mfma_f32_32x32x16_bf16 v[2:17], v[58:61], v[90:93], v[2:17]
	v_mfma_f32_32x32x16_bf16 v[2:17], v[62:65], v[182:185], v[2:17]
